# GDN right-hand sides: 24 LDS reads of a lane issued up front
# speedup vs baseline: 1.0032x; 1.0032x over previous
; #define LAS __attribute__((address_space(3)))
; #define LDS_WAIT() asm volatile("s_waitcnt lgkmcnt(0)" ::: "memory")
; DI void gdn_scan_block(LAS unsigned char* lds, int c, const float* P, const GdnPar& pr, float* ORAW, int tid, int lane, int wave) {
;     ...
;         if (wave < 4) {
;             const int cw16 = 16 * wave;
; #pragma unroll
;             for (int tb = 0; tb < 2; ++tb)
; #pragma unroll
;                 for (int i = 0; i < 4; ++i) { const int t = 16 * tb + 4 * g + i;
;                     RH[t * 64 + cw16 + m] = AB_[2 * t + 1] * (V_[t * 64 + cw16 + m] - __expf(GC_[t]) * P0a[tb][i]); }
;             LDS_WAIT(); asm volatile("" ::: "memory");
;             if (lane < 16) {
;                 float cc[32];
;                 const int rowi = cw16 + lane;
; #pragma unroll
;                 for (int tb8 = 0; tb8 < 4; ++tb8) {
;                     float acc[8];
; #pragma unroll
;                     for (int r = 0; r < 8; ++r) acc[r] = RH[(8 * tb8 + r) * 64 + rowi];
; #pragma unroll
;                     for (int jb = 0; jb < tb8; ++jb)
; #pragma unroll
;                         for (int r = 0; r < 8; ++r) { const f32x4 b0 = *(const LAS f32x4*)(BM + (8 * tb8 + r) * 32 + 8 * jb), b1 = *(const LAS f32x4*)(BM + (8 * tb8 + r) * 32 + 8 * jb + 4);
;                             acc[r] -= ((b0[0] * cc[8 * jb] + b0[1] * cc[8 * jb + 1]) + (b0[2] * cc[8 * jb + 2] + b0[3] * cc[8 * jb + 3])) + ((b1[0] * cc[8 * jb + 4] + b1[1] * cc[8 * jb + 5]) + (b1[2] * cc[8 * jb + 6] + b1[3] * cc[8 * jb + 7])); }
; #pragma unroll
;                     for (int rh = 0; rh < 2; ++rh) {
;                         f32x4 d0[4], d1[4];
; #pragma unroll
;                         for (int r = 0; r < 4; ++r) { d0[r] = *(const LAS f32x4*)(BM + (8 * tb8 + 4 * rh + r) * 32 + 8 * tb8); if (rh) d1[r] = *(const LAS f32x4*)(BM + (8 * tb8 + 4 * rh + r) * 32 + 8 * tb8 + 4); }
; #pragma unroll
;                         for (int r = 0; r < 4; ++r) { float av = acc[4 * rh + r];
; #pragma unroll
;                             for (int q = 0; q < 8; ++q) if (q < 4 * rh + r) av -= (q < 4 ? d0[r][q & 3] : d1[r][q & 3]) * cc[8 * tb8 + q];
;                             cc[8 * tb8 + 4 * rh + r] = av; CC[(8 * tb8 + 4 * rh + r) * 64 + rowi] = av; }
;                     }
;                 }
.LBB0_912:
	s_or_b64 exec, exec, s[34:35]
	ds_write_b32 v188, v72 offset:55040
	s_waitcnt lgkmcnt(0)
	s_barrier
	s_and_b64 vcc, exec, s[94:95]
	s_cbranch_vccz .LBB0_889
	ds_read_b32 v189, v178 offset:42240
	ds_read_b32 v190, v178 offset:42244
	ds_read_b32 v191, v178 offset:42248
	ds_read_b32 v192, v178 offset:42252
	ds_read_b32 v193, v178 offset:42304
	ds_read_b32 v194, v178 offset:42308
	ds_read_b32 v195, v178 offset:42312
	ds_read_b32 v196, v178 offset:42316
	ds_read_b32 v197, v140 offset:33792
	ds_read_b32 v198, v141 offset:33792
	ds_read_b32 v199, v142 offset:33792
	ds_read_b32 v200, v143 offset:33792
	s_waitcnt lgkmcnt(4)
	v_mul_f32_e32 v189, 0x3fb8aa3b, v189
	v_mul_f32_e32 v190, 0x3fb8aa3b, v190
	v_mul_f32_e32 v191, 0x3fb8aa3b, v191
	v_mul_f32_e32 v192, 0x3fb8aa3b, v192
	v_mul_f32_e32 v193, 0x3fb8aa3b, v193
	v_mul_f32_e32 v194, 0x3fb8aa3b, v194
	v_mul_f32_e32 v195, 0x3fb8aa3b, v195
	v_mul_f32_e32 v196, 0x3fb8aa3b, v196
	v_exp_f32_e32 v189, v189
	v_exp_f32_e32 v190, v190
	v_exp_f32_e32 v191, v191
	v_exp_f32_e32 v192, v192
	v_exp_f32_e32 v193, v193
	v_exp_f32_e32 v194, v194
	v_exp_f32_e32 v195, v195
	v_exp_f32_e32 v196, v196
	ds_read_b32 v201, v144 offset:33792
	ds_read_b32 v202, v145 offset:33792
	ds_read_b32 v203, v146 offset:33792
	ds_read_b32 v204, v147 offset:33792
	ds_read_b32 v208, v139 offset:41988
	ds_read_b32 v209, v179 offset:41988
	ds_read_b32 v210, v180 offset:41988
	ds_read_b32 v211, v181 offset:41988
	ds_read_b32 v212, v182 offset:41988
	ds_read_b32 v213, v183 offset:41988
	ds_read_b32 v214, v184 offset:41988
	ds_read_b32 v215, v185 offset:41988
	s_waitcnt lgkmcnt(7)
	v_fma_f32 v72, -v56, v189, v197
	v_mul_f32_e32 v72, v208, v72
	ds_write_b32 v140, v72 offset:59264
	s_waitcnt lgkmcnt(7)
	v_fma_f32 v72, -v57, v190, v198
	v_mul_f32_e32 v72, v209, v72
	ds_write_b32 v141, v72 offset:59264
	s_waitcnt lgkmcnt(7)
	v_fma_f32 v72, -v58, v191, v199
	v_mul_f32_e32 v72, v210, v72
	ds_write_b32 v142, v72 offset:59264
	s_waitcnt lgkmcnt(7)
	v_fma_f32 v72, -v59, v192, v200
	v_mul_f32_e32 v72, v211, v72
	ds_write_b32 v143, v72 offset:59264
	s_waitcnt lgkmcnt(7)
	v_fma_f32 v72, -v60, v193, v201
	v_mul_f32_e32 v72, v212, v72
	ds_write_b32 v144, v72 offset:59264
	s_waitcnt lgkmcnt(7)
	v_fma_f32 v72, -v61, v194, v202
	v_mul_f32_e32 v72, v213, v72
	ds_write_b32 v145, v72 offset:59264
	s_waitcnt lgkmcnt(7)
	v_fma_f32 v72, -v62, v195, v203
	v_mul_f32_e32 v72, v214, v72
	ds_write_b32 v146, v72 offset:59264
	s_waitcnt lgkmcnt(7)
	v_fma_f32 v72, -v63, v196, v204
	v_mul_f32_e32 v72, v215, v72
	ds_write_b32 v147, v72 offset:59264
	s_waitcnt lgkmcnt(0)
	s_and_saveexec_b64 s[34:35], s[8:9]
	s_cbranch_execz .LBB0_888
	v_mov_b32_e32 v128, s78
	ds_read2st64_b32 v[80:81], v132 offset0:0 offset1:1
	ds_read2st64_b32 v[104:105], v132 offset0:2 offset1:3
	ds_read_b128 v[72:75], v128 offset:51072
	ds_read_b128 v[76:79], v128 offset:51200
	ds_read_b128 v[100:103], v128 offset:51328
	ds_read_b128 v[208:211], v128 offset:51456
	s_waitcnt lgkmcnt(3)
	v_mov_b32_e32 v189, v80
	v_fma_f32 v190, -v72, v189, v81
	ds_read_b128 v[212:215], v128 offset:51584
	ds_write2st64_b32 v133, v189, v190 offset0:0 offset1:1
	ds_read2st64_b32 v[130:131], v132 offset0:4 offset1:5
	s_waitcnt lgkmcnt(4)
	v_fma_f32 v104, -v76, v189, v104
	v_fma_f32 v105, -v100, v189, v105
	v_fma_f32 v191, -v77, v190, v104
	v_fma_f32 v105, -v101, v190, v105
	v_fma_f32 v192, -v102, v191, v105
	ds_read_b128 v[72:75], v128 offset:51600
	ds_read_b128 v[76:79], v128 offset:51712
	ds_write2st64_b32 v133, v191, v192 offset0:2 offset1:3
	ds_read2st64_b32 v[80:81], v132 offset0:6 offset1:7
	s_waitcnt lgkmcnt(4)
	v_fma_f32 v130, -v208, v189, v130
	v_fma_f32 v131, -v212, v189, v131
	v_fma_f32 v130, -v209, v190, v130
	v_fma_f32 v131, -v213, v190, v131
	v_fma_f32 v130, -v210, v191, v130
	v_fma_f32 v131, -v214, v191, v131
	v_fma_f32 v193, -v211, v192, v130
	v_fma_f32 v131, -v215, v192, v131
	ds_read_b128 v[100:103], v128 offset:51840
	ds_read_b128 v[208:211], v128 offset:51728
	s_waitcnt lgkmcnt(5)
	v_fma_f32 v194, -v72, v193, v131
	ds_read_b128 v[212:215], v128 offset:51856
	ds_write2st64_b32 v133, v193, v194 offset0:4 offset1:5
	ds_read2st64_b32 v[104:105], v132 offset0:8 offset1:9
	s_waitcnt lgkmcnt(4)
	v_fma_f32 v80, -v76, v189, v80
	v_fma_f32 v81, -v100, v189, v81
	v_fma_f32 v80, -v77, v190, v80
	v_fma_f32 v81, -v101, v190, v81
	v_fma_f32 v80, -v78, v191, v80
	v_fma_f32 v81, -v102, v191, v81
	v_fma_f32 v80, -v79, v192, v80
	v_fma_f32 v81, -v103, v192, v81
	ds_read_b128 v[72:75], v128 offset:51968
	ds_read_b128 v[76:79], v128 offset:52096
	s_waitcnt lgkmcnt(4)
	v_fma_f32 v80, -v208, v193, v80
	v_fma_f32 v81, -v212, v193, v81
	v_fma_f32 v195, -v209, v194, v80
	v_fma_f32 v81, -v213, v194, v81
	v_fma_f32 v196, -v214, v195, v81
	ds_read_b128 v[100:103], v128 offset:51984
	ds_read_b128 v[208:211], v128 offset:52112
	ds_write2st64_b32 v133, v195, v196 offset0:6 offset1:7
	ds_read2st64_b32 v[130:131], v132 offset0:10 offset1:11
	s_waitcnt lgkmcnt(4)
	v_fma_f32 v104, -v72, v189, v104
	v_fma_f32 v105, -v76, v189, v105
	v_fma_f32 v104, -v73, v190, v104
	v_fma_f32 v105, -v77, v190, v105
	v_fma_f32 v104, -v74, v191, v104
	v_fma_f32 v105, -v78, v191, v105
	v_fma_f32 v104, -v75, v192, v104
	v_fma_f32 v105, -v79, v192, v105
	ds_read_b128 v[212:215], v128 offset:52128
	ds_read_b128 v[72:75], v128 offset:52224
	s_waitcnt lgkmcnt(4)
	v_fma_f32 v104, -v100, v193, v104
	v_fma_f32 v105, -v208, v193, v105
	v_fma_f32 v104, -v101, v194, v104
	v_fma_f32 v105, -v209, v194, v105
	v_fma_f32 v104, -v102, v195, v104
	v_fma_f32 v105, -v210, v195, v105
	v_fma_f32 v197, -v103, v196, v104
	v_fma_f32 v105, -v211, v196, v105
	ds_read_b128 v[76:79], v128 offset:52352
	ds_read_b128 v[100:103], v128 offset:52240
	s_waitcnt lgkmcnt(3)
; #define LAS __attribute__((address_space(3)))
; DI void gdn_scan_block(LAS unsigned char* lds, int c, const float* P, const GdnPar& pr, float* ORAW, int tid, int lane, int wave) {
;     ...
;             if (lane < 16) {
;                 float cc[32];
;                 const int rowi = cw16 + lane;
; #pragma unroll
;                 for (int tb8 = 0; tb8 < 4; ++tb8) {
;                     float acc[8];
; #pragma unroll
;                     for (int r = 0; r < 8; ++r) acc[r] = RH[(8 * tb8 + r) * 64 + rowi];
; #pragma unroll
;                     for (int jb = 0; jb < tb8; ++jb)
; #pragma unroll
;                         for (int r = 0; r < 8; ++r) { const f32x4 b0 = *(const LAS f32x4*)(BM + (8 * tb8 + r) * 32 + 8 * jb), b1 = *(const LAS f32x4*)(BM + (8 * tb8 + r) * 32 + 8 * jb + 4);
;                             acc[r] -= ((b0[0] * cc[8 * jb] + b0[1] * cc[8 * jb + 1]) + (b0[2] * cc[8 * jb + 2] + b0[3] * cc[8 * jb + 3])) + ((b1[0] * cc[8 * jb + 4] + b1[1] * cc[8 * jb + 5]) + (b1[2] * cc[8 * jb + 6] + b1[3] * cc[8 * jb + 7])); }
; #pragma unroll
;                     for (int rh = 0; rh < 2; ++rh) {
;                         f32x4 d0[4], d1[4];
; #pragma unroll
;                         for (int r = 0; r < 4; ++r) { d0[r] = *(const LAS f32x4*)(BM + (8 * tb8 + 4 * rh + r) * 32 + 8 * tb8); if (rh) d1[r] = *(const LAS f32x4*)(BM + (8 * tb8 + 4 * rh + r) * 32 + 8 * tb8 + 4); }
; #pragma unroll
;                         for (int r = 0; r < 4; ++r) { float av = acc[4 * rh + r];
; #pragma unroll
;                             for (int q = 0; q < 8; ++q) if (q < 4 * rh + r) av -= (q < 4 ? d0[r][q & 3] : d1[r][q & 3]) * cc[8 * tb8 + q];
;                             cc[8 * tb8 + 4 * rh + r] = av; CC[(8 * tb8 + 4 * rh + r) * 64 + rowi] = av; }
;                     }
;                 }
	v_fma_f32 v198, -v212, v197, v105
	ds_read_b128 v[208:211], v128 offset:52368
	ds_write2st64_b32 v133, v197, v198 offset0:8 offset1:9
	ds_read2st64_b32 v[80:81], v132 offset0:12 offset1:13
	s_waitcnt lgkmcnt(4)
	v_fma_f32 v130, -v72, v189, v130
	v_fma_f32 v131, -v76, v189, v131
	v_fma_f32 v130, -v73, v190, v130
	v_fma_f32 v131, -v77, v190, v131
	v_fma_f32 v130, -v74, v191, v130
	v_fma_f32 v131, -v78, v191, v131
	v_fma_f32 v130, -v75, v192, v130
	v_fma_f32 v131, -v79, v192, v131
	ds_read_b128 v[212:215], v128 offset:52256
	ds_read_b128 v[72:75], v128 offset:52384
	s_waitcnt lgkmcnt(4)
	v_fma_f32 v130, -v100, v193, v130
	v_fma_f32 v131, -v208, v193, v131
	v_fma_f32 v130, -v101, v194, v130
	v_fma_f32 v131, -v209, v194, v131
	v_fma_f32 v130, -v102, v195, v130
	v_fma_f32 v131, -v210, v195, v131
	v_fma_f32 v130, -v103, v196, v130
	v_fma_f32 v131, -v211, v196, v131
	ds_read_b128 v[76:79], v128 offset:52480
	ds_read_b128 v[100:103], v128 offset:52608
	s_waitcnt lgkmcnt(2)
	v_fma_f32 v130, -v212, v197, v130
	v_fma_f32 v131, -v72, v197, v131
	v_fma_f32 v199, -v213, v198, v130
	v_fma_f32 v131, -v73, v198, v131
	v_fma_f32 v200, -v74, v199, v131
	ds_read_b128 v[208:211], v128 offset:52496
	ds_read_b128 v[212:215], v128 offset:52624
	ds_write2st64_b32 v133, v199, v200 offset0:10 offset1:11
	ds_read2st64_b32 v[104:105], v132 offset0:14 offset1:15
	s_waitcnt lgkmcnt(4)
	v_fma_f32 v80, -v76, v189, v80
	v_fma_f32 v81, -v100, v189, v81
	v_fma_f32 v80, -v77, v190, v80
	v_fma_f32 v81, -v101, v190, v81
	v_fma_f32 v80, -v78, v191, v80
	v_fma_f32 v81, -v102, v191, v81
	v_fma_f32 v80, -v79, v192, v80
	v_fma_f32 v81, -v103, v192, v81
	ds_read_b128 v[72:75], v128 offset:52512
	ds_read_b128 v[76:79], v128 offset:52640
	s_waitcnt lgkmcnt(4)
	v_fma_f32 v80, -v208, v193, v80
	v_fma_f32 v81, -v212, v193, v81
	v_fma_f32 v80, -v209, v194, v80
	v_fma_f32 v81, -v213, v194, v81
	v_fma_f32 v80, -v210, v195, v80
	v_fma_f32 v81, -v214, v195, v81
	v_fma_f32 v80, -v211, v196, v80
	v_fma_f32 v81, -v215, v196, v81
	ds_read_b128 v[100:103], v128 offset:52656
	ds_read_b128 v[208:211], v128 offset:52736
	s_waitcnt lgkmcnt(2)
	v_fma_f32 v80, -v72, v197, v80
	v_fma_f32 v81, -v76, v197, v81
	v_fma_f32 v80, -v73, v198, v80
	v_fma_f32 v81, -v77, v198, v81
	v_fma_f32 v80, -v74, v199, v80
	v_fma_f32 v81, -v78, v199, v81
	v_fma_f32 v201, -v75, v200, v80
	v_fma_f32 v81, -v79, v200, v81
	ds_read_b128 v[212:215], v128 offset:52864
	ds_read_b128 v[72:75], v128 offset:52752
	s_waitcnt lgkmcnt(3)
	v_fma_f32 v202, -v100, v201, v81
	ds_read_b128 v[76:79], v128 offset:52880
	ds_write2st64_b32 v133, v201, v202 offset0:12 offset1:13
	ds_read2st64_b32 v[130:131], v132 offset0:16 offset1:17
	s_waitcnt lgkmcnt(4)
	v_fma_f32 v104, -v208, v189, v104
	v_fma_f32 v105, -v212, v189, v105
	v_fma_f32 v104, -v209, v190, v104
	v_fma_f32 v105, -v213, v190, v105
	v_fma_f32 v104, -v210, v191, v104
	v_fma_f32 v105, -v214, v191, v105
	v_fma_f32 v104, -v211, v192, v104
	v_fma_f32 v105, -v215, v192, v105
	ds_read_b128 v[100:103], v128 offset:52768
	ds_read_b128 v[208:211], v128 offset:52896
	s_waitcnt lgkmcnt(4)
	v_fma_f32 v104, -v72, v193, v104
	v_fma_f32 v105, -v76, v193, v105
	v_fma_f32 v104, -v73, v194, v104
	v_fma_f32 v105, -v77, v194, v105
	v_fma_f32 v104, -v74, v195, v104
	v_fma_f32 v105, -v78, v195, v105
	v_fma_f32 v104, -v75, v196, v104
	v_fma_f32 v105, -v79, v196, v105
	ds_read_b128 v[212:215], v128 offset:52784
	ds_read_b128 v[72:75], v128 offset:52912
	s_waitcnt lgkmcnt(2)
	v_fma_f32 v104, -v100, v197, v104
	v_fma_f32 v105, -v208, v197, v105
	v_fma_f32 v104, -v101, v198, v104
	v_fma_f32 v105, -v209, v198, v105
	v_fma_f32 v104, -v102, v199, v104
	v_fma_f32 v105, -v210, v199, v105
	v_fma_f32 v104, -v103, v200, v104
	v_fma_f32 v105, -v211, v200, v105
	ds_read_b128 v[76:79], v128 offset:52992
	ds_read_b128 v[100:103], v128 offset:53120
	s_waitcnt lgkmcnt(2)
	v_fma_f32 v104, -v212, v201, v104
	v_fma_f32 v105, -v72, v201, v105
	v_fma_f32 v203, -v213, v202, v104
	v_fma_f32 v105, -v73, v202, v105
	v_fma_f32 v204, -v74, v203, v105
	ds_read_b128 v[208:211], v128 offset:53008
	ds_read_b128 v[212:215], v128 offset:53136
	ds_write2st64_b32 v133, v203, v204 offset0:14 offset1:15
	ds_read2st64_b32 v[80:81], v132 offset0:18 offset1:19
	s_waitcnt lgkmcnt(4)
	v_fma_f32 v130, -v76, v189, v130
	v_fma_f32 v131, -v100, v189, v131
	v_fma_f32 v130, -v77, v190, v130
	v_fma_f32 v131, -v101, v190, v131
	v_fma_f32 v130, -v78, v191, v130
	v_fma_f32 v131, -v102, v191, v131
	v_fma_f32 v130, -v79, v192, v130
	v_fma_f32 v131, -v103, v192, v131
	ds_read_b128 v[72:75], v128 offset:53024
	ds_read_b128 v[76:79], v128 offset:53152
	s_waitcnt lgkmcnt(4)
	v_fma_f32 v130, -v208, v193, v130
	v_fma_f32 v131, -v212, v193, v131
	v_fma_f32 v130, -v209, v194, v130
	v_fma_f32 v131, -v213, v194, v131
	v_fma_f32 v130, -v210, v195, v130
	v_fma_f32 v131, -v214, v195, v131
	v_fma_f32 v130, -v211, v196, v130
	v_fma_f32 v131, -v215, v196, v131
	ds_read_b128 v[100:103], v128 offset:53040
	ds_read_b128 v[208:211], v128 offset:53168
	s_waitcnt lgkmcnt(2)
	v_fma_f32 v130, -v72, v197, v130
	v_fma_f32 v131, -v76, v197, v131
	v_fma_f32 v130, -v73, v198, v130
	v_fma_f32 v131, -v77, v198, v131
	v_fma_f32 v130, -v74, v199, v130
	v_fma_f32 v131, -v78, v199, v131
	v_fma_f32 v130, -v75, v200, v130
	v_fma_f32 v131, -v79, v200, v131
	ds_read_b128 v[212:215], v128 offset:53184
	ds_read_b128 v[72:75], v128 offset:53248
	s_waitcnt lgkmcnt(2)
	v_fma_f32 v130, -v100, v201, v130
	v_fma_f32 v131, -v208, v201, v131
	v_fma_f32 v130, -v101, v202, v130
	v_fma_f32 v131, -v209, v202, v131
	v_fma_f32 v130, -v102, v203, v130
	v_fma_f32 v131, -v210, v203, v131
	v_fma_f32 v205, -v103, v204, v130
	v_fma_f32 v131, -v211, v204, v131
	ds_read_b128 v[76:79], v128 offset:53376
	ds_read_b128 v[100:103], v128 offset:53264
	s_waitcnt lgkmcnt(3)
; #define LAS __attribute__((address_space(3)))
; DI void gdn_scan_block(LAS unsigned char* lds, int c, const float* P, const GdnPar& pr, float* ORAW, int tid, int lane, int wave) {
;     ...
;             if (lane < 16) {
;                 float cc[32];
;                 const int rowi = cw16 + lane;
; #pragma unroll
;                 for (int tb8 = 0; tb8 < 4; ++tb8) {
;                     float acc[8];
; #pragma unroll
;                     for (int r = 0; r < 8; ++r) acc[r] = RH[(8 * tb8 + r) * 64 + rowi];
; #pragma unroll
;                     for (int jb = 0; jb < tb8; ++jb)
; #pragma unroll
;                         for (int r = 0; r < 8; ++r) { const f32x4 b0 = *(const LAS f32x4*)(BM + (8 * tb8 + r) * 32 + 8 * jb), b1 = *(const LAS f32x4*)(BM + (8 * tb8 + r) * 32 + 8 * jb + 4);
;                             acc[r] -= ((b0[0] * cc[8 * jb] + b0[1] * cc[8 * jb + 1]) + (b0[2] * cc[8 * jb + 2] + b0[3] * cc[8 * jb + 3])) + ((b1[0] * cc[8 * jb + 4] + b1[1] * cc[8 * jb + 5]) + (b1[2] * cc[8 * jb + 6] + b1[3] * cc[8 * jb + 7])); }
; #pragma unroll
;                     for (int rh = 0; rh < 2; ++rh) {
;                         f32x4 d0[4], d1[4];
; #pragma unroll
;                         for (int r = 0; r < 4; ++r) { d0[r] = *(const LAS f32x4*)(BM + (8 * tb8 + 4 * rh + r) * 32 + 8 * tb8); if (rh) d1[r] = *(const LAS f32x4*)(BM + (8 * tb8 + 4 * rh + r) * 32 + 8 * tb8 + 4); }
; #pragma unroll
;                         for (int r = 0; r < 4; ++r) { float av = acc[4 * rh + r];
; #pragma unroll
;                             for (int q = 0; q < 8; ++q) if (q < 4 * rh + r) av -= (q < 4 ? d0[r][q & 3] : d1[r][q & 3]) * cc[8 * tb8 + q];
;                             cc[8 * tb8 + 4 * rh + r] = av; CC[(8 * tb8 + 4 * rh + r) * 64 + rowi] = av; }
;                     }
;                 }
	v_fma_f32 v216, -v212, v205, v131
	ds_read_b128 v[208:211], v128 offset:53392
	ds_write2st64_b32 v133, v205, v216 offset0:16 offset1:17
	ds_read2st64_b32 v[104:105], v132 offset0:20 offset1:21
	s_waitcnt lgkmcnt(4)
	v_fma_f32 v80, -v72, v189, v80
	v_fma_f32 v81, -v76, v189, v81
	v_fma_f32 v80, -v73, v190, v80
	v_fma_f32 v81, -v77, v190, v81
	v_fma_f32 v80, -v74, v191, v80
	v_fma_f32 v81, -v78, v191, v81
	v_fma_f32 v80, -v75, v192, v80
	v_fma_f32 v81, -v79, v192, v81
	ds_read_b128 v[212:215], v128 offset:53280
	ds_read_b128 v[72:75], v128 offset:53408
	s_waitcnt lgkmcnt(4)
	v_fma_f32 v80, -v100, v193, v80
	v_fma_f32 v81, -v208, v193, v81
	v_fma_f32 v80, -v101, v194, v80
	v_fma_f32 v81, -v209, v194, v81
	v_fma_f32 v80, -v102, v195, v80
	v_fma_f32 v81, -v210, v195, v81
	v_fma_f32 v80, -v103, v196, v80
	v_fma_f32 v81, -v211, v196, v81
	ds_read_b128 v[76:79], v128 offset:53296
	ds_read_b128 v[100:103], v128 offset:53424
	s_waitcnt lgkmcnt(2)
	v_fma_f32 v80, -v212, v197, v80
	v_fma_f32 v81, -v72, v197, v81
	v_fma_f32 v80, -v213, v198, v80
	v_fma_f32 v81, -v73, v198, v81
	v_fma_f32 v80, -v214, v199, v80
	v_fma_f32 v81, -v74, v199, v81
	v_fma_f32 v80, -v215, v200, v80
	v_fma_f32 v81, -v75, v200, v81
	ds_read_b128 v[208:211], v128 offset:53312
	ds_read_b128 v[212:215], v128 offset:53440
	s_waitcnt lgkmcnt(2)
	v_fma_f32 v80, -v76, v201, v80
	v_fma_f32 v81, -v100, v201, v81
	v_fma_f32 v80, -v77, v202, v80
	v_fma_f32 v81, -v101, v202, v81
	v_fma_f32 v80, -v78, v203, v80
	v_fma_f32 v81, -v102, v203, v81
	v_fma_f32 v80, -v79, v204, v80
	v_fma_f32 v81, -v103, v204, v81
	ds_read_b128 v[72:75], v128 offset:53504
	ds_read_b128 v[76:79], v128 offset:53632
	s_waitcnt lgkmcnt(2)
	v_fma_f32 v80, -v208, v205, v80
	v_fma_f32 v81, -v212, v205, v81
	v_fma_f32 v217, -v209, v216, v80
	v_fma_f32 v81, -v213, v216, v81
	v_fma_f32 v218, -v214, v217, v81
	ds_read_b128 v[100:103], v128 offset:53520
	ds_read_b128 v[208:211], v128 offset:53648
	ds_write2st64_b32 v133, v217, v218 offset0:18 offset1:19
	ds_read2st64_b32 v[130:131], v132 offset0:22 offset1:23
	s_waitcnt lgkmcnt(4)
	v_fma_f32 v104, -v72, v189, v104
	v_fma_f32 v105, -v76, v189, v105
	v_fma_f32 v104, -v73, v190, v104
	v_fma_f32 v105, -v77, v190, v105
	v_fma_f32 v104, -v74, v191, v104
	v_fma_f32 v105, -v78, v191, v105
	v_fma_f32 v104, -v75, v192, v104
	v_fma_f32 v105, -v79, v192, v105
	ds_read_b128 v[212:215], v128 offset:53536
	ds_read_b128 v[72:75], v128 offset:53664
	s_waitcnt lgkmcnt(4)
	v_fma_f32 v104, -v100, v193, v104
	v_fma_f32 v105, -v208, v193, v105
	v_fma_f32 v104, -v101, v194, v104
	v_fma_f32 v105, -v209, v194, v105
	v_fma_f32 v104, -v102, v195, v104
	v_fma_f32 v105, -v210, v195, v105
	v_fma_f32 v104, -v103, v196, v104
	v_fma_f32 v105, -v211, v196, v105
	ds_read_b128 v[76:79], v128 offset:53552
	ds_read_b128 v[100:103], v128 offset:53680
	s_waitcnt lgkmcnt(2)
	v_fma_f32 v104, -v212, v197, v104
	v_fma_f32 v105, -v72, v197, v105
	v_fma_f32 v104, -v213, v198, v104
	v_fma_f32 v105, -v73, v198, v105
	v_fma_f32 v104, -v214, v199, v104
	v_fma_f32 v105, -v74, v199, v105
	v_fma_f32 v104, -v215, v200, v104
	v_fma_f32 v105, -v75, v200, v105
	ds_read_b128 v[208:211], v128 offset:53568
	ds_read_b128 v[212:215], v128 offset:53696
	s_waitcnt lgkmcnt(2)
	v_fma_f32 v104, -v76, v201, v104
	v_fma_f32 v105, -v100, v201, v105
	v_fma_f32 v104, -v77, v202, v104
	v_fma_f32 v105, -v101, v202, v105
	v_fma_f32 v104, -v78, v203, v104
	v_fma_f32 v105, -v102, v203, v105
	v_fma_f32 v104, -v79, v204, v104
	v_fma_f32 v105, -v103, v204, v105
	ds_read_b128 v[72:75], v128 offset:53712
	ds_read_b128 v[76:79], v128 offset:53760
	s_waitcnt lgkmcnt(2)
	v_fma_f32 v104, -v208, v205, v104
	v_fma_f32 v105, -v212, v205, v105
	v_fma_f32 v104, -v209, v216, v104
	v_fma_f32 v105, -v213, v216, v105
	v_fma_f32 v104, -v210, v217, v104
	v_fma_f32 v105, -v214, v217, v105
	v_fma_f32 v219, -v211, v218, v104
	v_fma_f32 v105, -v215, v218, v105
	ds_read_b128 v[100:103], v128 offset:53888
	ds_read_b128 v[208:211], v128 offset:53776
	s_waitcnt lgkmcnt(3)
	v_fma_f32 v220, -v72, v219, v105
	ds_read_b128 v[212:215], v128 offset:53904
	ds_write2st64_b32 v133, v219, v220 offset0:20 offset1:21
	ds_read2st64_b32 v[80:81], v132 offset0:24 offset1:25
	s_waitcnt lgkmcnt(4)
	v_fma_f32 v130, -v76, v189, v130
	v_fma_f32 v131, -v100, v189, v131
	v_fma_f32 v130, -v77, v190, v130
	v_fma_f32 v131, -v101, v190, v131
	v_fma_f32 v130, -v78, v191, v130
	v_fma_f32 v131, -v102, v191, v131
	v_fma_f32 v130, -v79, v192, v130
	v_fma_f32 v131, -v103, v192, v131
	ds_read_b128 v[72:75], v128 offset:53792
	ds_read_b128 v[76:79], v128 offset:53920
	s_waitcnt lgkmcnt(4)
	v_fma_f32 v130, -v208, v193, v130
	v_fma_f32 v131, -v212, v193, v131
	v_fma_f32 v130, -v209, v194, v130
	v_fma_f32 v131, -v213, v194, v131
	v_fma_f32 v130, -v210, v195, v130
	v_fma_f32 v131, -v214, v195, v131
	v_fma_f32 v130, -v211, v196, v130
	v_fma_f32 v131, -v215, v196, v131
	ds_read_b128 v[100:103], v128 offset:53808
	ds_read_b128 v[208:211], v128 offset:53936
	s_waitcnt lgkmcnt(2)
	v_fma_f32 v130, -v72, v197, v130
	v_fma_f32 v131, -v76, v197, v131
	v_fma_f32 v130, -v73, v198, v130
	v_fma_f32 v131, -v77, v198, v131
	v_fma_f32 v130, -v74, v199, v130
	v_fma_f32 v131, -v78, v199, v131
	v_fma_f32 v130, -v75, v200, v130
	v_fma_f32 v131, -v79, v200, v131
	ds_read_b128 v[212:215], v128 offset:53824
	ds_read_b128 v[72:75], v128 offset:53952
	s_waitcnt lgkmcnt(2)
	v_fma_f32 v130, -v100, v201, v130
	v_fma_f32 v131, -v208, v201, v131
	v_fma_f32 v130, -v101, v202, v130
	v_fma_f32 v131, -v209, v202, v131
	v_fma_f32 v130, -v102, v203, v130
	v_fma_f32 v131, -v210, v203, v131
	v_fma_f32 v130, -v103, v204, v130
	v_fma_f32 v131, -v211, v204, v131
	ds_read_b128 v[76:79], v128 offset:53840
	ds_read_b128 v[100:103], v128 offset:53968
	s_waitcnt lgkmcnt(2)
; #define LAS __attribute__((address_space(3)))
; DI void gdn_scan_block(LAS unsigned char* lds, int c, const float* P, const GdnPar& pr, float* ORAW, int tid, int lane, int wave) {
;     ...
;             if (lane < 16) {
;                 float cc[32];
;                 const int rowi = cw16 + lane;
; #pragma unroll
;                 for (int tb8 = 0; tb8 < 4; ++tb8) {
;                     float acc[8];
; #pragma unroll
;                     for (int r = 0; r < 8; ++r) acc[r] = RH[(8 * tb8 + r) * 64 + rowi];
; #pragma unroll
;                     for (int jb = 0; jb < tb8; ++jb)
; #pragma unroll
;                         for (int r = 0; r < 8; ++r) { const f32x4 b0 = *(const LAS f32x4*)(BM + (8 * tb8 + r) * 32 + 8 * jb), b1 = *(const LAS f32x4*)(BM + (8 * tb8 + r) * 32 + 8 * jb + 4);
;                             acc[r] -= ((b0[0] * cc[8 * jb] + b0[1] * cc[8 * jb + 1]) + (b0[2] * cc[8 * jb + 2] + b0[3] * cc[8 * jb + 3])) + ((b1[0] * cc[8 * jb + 4] + b1[1] * cc[8 * jb + 5]) + (b1[2] * cc[8 * jb + 6] + b1[3] * cc[8 * jb + 7])); }
; #pragma unroll
;                     for (int rh = 0; rh < 2; ++rh) {
;                         f32x4 d0[4], d1[4];
; #pragma unroll
;                         for (int r = 0; r < 4; ++r) { d0[r] = *(const LAS f32x4*)(BM + (8 * tb8 + 4 * rh + r) * 32 + 8 * tb8); if (rh) d1[r] = *(const LAS f32x4*)(BM + (8 * tb8 + 4 * rh + r) * 32 + 8 * tb8 + 4); }
; #pragma unroll
;                         for (int r = 0; r < 4; ++r) { float av = acc[4 * rh + r];
; #pragma unroll
;                             for (int q = 0; q < 8; ++q) if (q < 4 * rh + r) av -= (q < 4 ? d0[r][q & 3] : d1[r][q & 3]) * cc[8 * tb8 + q];
;                             cc[8 * tb8 + 4 * rh + r] = av; CC[(8 * tb8 + 4 * rh + r) * 64 + rowi] = av; }
;                     }
;                 }
	v_fma_f32 v130, -v212, v205, v130
	v_fma_f32 v131, -v72, v205, v131
	v_fma_f32 v130, -v213, v216, v130
	v_fma_f32 v131, -v73, v216, v131
	v_fma_f32 v130, -v214, v217, v130
	v_fma_f32 v131, -v74, v217, v131
	v_fma_f32 v130, -v215, v218, v130
	v_fma_f32 v131, -v75, v218, v131
	ds_read_b128 v[208:211], v128 offset:54016
	ds_read_b128 v[212:215], v128 offset:54144
	s_waitcnt lgkmcnt(2)
	v_fma_f32 v130, -v76, v219, v130
	v_fma_f32 v131, -v100, v219, v131
	v_fma_f32 v221, -v77, v220, v130
	v_fma_f32 v131, -v101, v220, v131
	v_fma_f32 v222, -v102, v221, v131
	ds_read_b128 v[72:75], v128 offset:54032
	ds_read_b128 v[76:79], v128 offset:54160
	ds_write2st64_b32 v133, v221, v222 offset0:22 offset1:23
	ds_read2st64_b32 v[104:105], v132 offset0:26 offset1:27
	s_waitcnt lgkmcnt(4)
	v_fma_f32 v80, -v208, v189, v80
	v_fma_f32 v81, -v212, v189, v81
	v_fma_f32 v80, -v209, v190, v80
	v_fma_f32 v81, -v213, v190, v81
	v_fma_f32 v80, -v210, v191, v80
	v_fma_f32 v81, -v214, v191, v81
	v_fma_f32 v80, -v211, v192, v80
	v_fma_f32 v81, -v215, v192, v81
	ds_read_b128 v[100:103], v128 offset:54048
	ds_read_b128 v[208:211], v128 offset:54176
	s_waitcnt lgkmcnt(4)
	v_fma_f32 v80, -v72, v193, v80
	v_fma_f32 v81, -v76, v193, v81
	v_fma_f32 v80, -v73, v194, v80
	v_fma_f32 v81, -v77, v194, v81
	v_fma_f32 v80, -v74, v195, v80
	v_fma_f32 v81, -v78, v195, v81
	v_fma_f32 v80, -v75, v196, v80
	v_fma_f32 v81, -v79, v196, v81
	ds_read_b128 v[212:215], v128 offset:54064
	ds_read_b128 v[72:75], v128 offset:54192
	s_waitcnt lgkmcnt(2)
	v_fma_f32 v80, -v100, v197, v80
	v_fma_f32 v81, -v208, v197, v81
	v_fma_f32 v80, -v101, v198, v80
	v_fma_f32 v81, -v209, v198, v81
	v_fma_f32 v80, -v102, v199, v80
	v_fma_f32 v81, -v210, v199, v81
	v_fma_f32 v80, -v103, v200, v80
	v_fma_f32 v81, -v211, v200, v81
	ds_read_b128 v[76:79], v128 offset:54080
	ds_read_b128 v[100:103], v128 offset:54208
	s_waitcnt lgkmcnt(2)
	v_fma_f32 v80, -v212, v201, v80
	v_fma_f32 v81, -v72, v201, v81
	v_fma_f32 v80, -v213, v202, v80
	v_fma_f32 v81, -v73, v202, v81
	v_fma_f32 v80, -v214, v203, v80
	v_fma_f32 v81, -v74, v203, v81
	v_fma_f32 v80, -v215, v204, v80
	v_fma_f32 v81, -v75, v204, v81
	ds_read_b128 v[208:211], v128 offset:54096
	ds_read_b128 v[212:215], v128 offset:54224
	s_waitcnt lgkmcnt(2)
	v_fma_f32 v80, -v76, v205, v80
	v_fma_f32 v81, -v100, v205, v81
	v_fma_f32 v80, -v77, v216, v80
	v_fma_f32 v81, -v101, v216, v81
	v_fma_f32 v80, -v78, v217, v80
	v_fma_f32 v81, -v102, v217, v81
	v_fma_f32 v80, -v79, v218, v80
	v_fma_f32 v81, -v103, v218, v81
	ds_read_b128 v[72:75], v128 offset:54240
	ds_read_b128 v[76:79], v128 offset:54272
	s_waitcnt lgkmcnt(2)
	v_fma_f32 v80, -v208, v219, v80
	v_fma_f32 v81, -v212, v219, v81
	v_fma_f32 v80, -v209, v220, v80
	v_fma_f32 v81, -v213, v220, v81
	v_fma_f32 v80, -v210, v221, v80
	v_fma_f32 v81, -v214, v221, v81
	v_fma_f32 v223, -v211, v222, v80
	v_fma_f32 v81, -v215, v222, v81
	ds_read_b128 v[100:103], v128 offset:54400
	ds_read_b128 v[208:211], v128 offset:54288
	s_waitcnt lgkmcnt(3)
	v_fma_f32 v224, -v72, v223, v81
	ds_read_b128 v[212:215], v128 offset:54416
	ds_write2st64_b32 v133, v223, v224 offset0:24 offset1:25
	ds_read2st64_b32 v[130:131], v132 offset0:28 offset1:29
	s_waitcnt lgkmcnt(4)
	v_fma_f32 v104, -v76, v189, v104
	v_fma_f32 v105, -v100, v189, v105
	v_fma_f32 v104, -v77, v190, v104
	v_fma_f32 v105, -v101, v190, v105
	v_fma_f32 v104, -v78, v191, v104
	v_fma_f32 v105, -v102, v191, v105
	v_fma_f32 v104, -v79, v192, v104
	v_fma_f32 v105, -v103, v192, v105
	ds_read_b128 v[72:75], v128 offset:54304
	ds_read_b128 v[76:79], v128 offset:54432
	s_waitcnt lgkmcnt(4)
	v_fma_f32 v104, -v208, v193, v104
	v_fma_f32 v105, -v212, v193, v105
	v_fma_f32 v104, -v209, v194, v104
	v_fma_f32 v105, -v213, v194, v105
	v_fma_f32 v104, -v210, v195, v104
	v_fma_f32 v105, -v214, v195, v105
	v_fma_f32 v104, -v211, v196, v104
	v_fma_f32 v105, -v215, v196, v105
	ds_read_b128 v[100:103], v128 offset:54320
	ds_read_b128 v[208:211], v128 offset:54448
	s_waitcnt lgkmcnt(2)
	v_fma_f32 v104, -v72, v197, v104
	v_fma_f32 v105, -v76, v197, v105
	v_fma_f32 v104, -v73, v198, v104
	v_fma_f32 v105, -v77, v198, v105
	v_fma_f32 v104, -v74, v199, v104
	v_fma_f32 v105, -v78, v199, v105
	v_fma_f32 v104, -v75, v200, v104
	v_fma_f32 v105, -v79, v200, v105
	ds_read_b128 v[212:215], v128 offset:54336
	ds_read_b128 v[72:75], v128 offset:54464
	s_waitcnt lgkmcnt(2)
	v_fma_f32 v104, -v100, v201, v104
	v_fma_f32 v105, -v208, v201, v105
	v_fma_f32 v104, -v101, v202, v104
	v_fma_f32 v105, -v209, v202, v105
	v_fma_f32 v104, -v102, v203, v104
	v_fma_f32 v105, -v210, v203, v105
	v_fma_f32 v104, -v103, v204, v104
	v_fma_f32 v105, -v211, v204, v105
	ds_read_b128 v[76:79], v128 offset:54352
	ds_read_b128 v[100:103], v128 offset:54480
	s_waitcnt lgkmcnt(2)
	v_fma_f32 v104, -v212, v205, v104
	v_fma_f32 v105, -v72, v205, v105
	v_fma_f32 v104, -v213, v216, v104
	v_fma_f32 v105, -v73, v216, v105
	v_fma_f32 v104, -v214, v217, v104
	v_fma_f32 v105, -v74, v217, v105
	v_fma_f32 v104, -v215, v218, v104
	v_fma_f32 v105, -v75, v218, v105
	ds_read_b128 v[208:211], v128 offset:54368
	ds_read_b128 v[212:215], v128 offset:54496
	s_waitcnt lgkmcnt(2)
	v_fma_f32 v104, -v76, v219, v104
	v_fma_f32 v105, -v100, v219, v105
	v_fma_f32 v104, -v77, v220, v104
	v_fma_f32 v105, -v101, v220, v105
	v_fma_f32 v104, -v78, v221, v104
	v_fma_f32 v105, -v102, v221, v105
	v_fma_f32 v104, -v79, v222, v104
	v_fma_f32 v105, -v103, v222, v105
	ds_read_b128 v[72:75], v128 offset:54528
	ds_read_b128 v[76:79], v128 offset:54656
	s_waitcnt lgkmcnt(2)
; #define LAS __attribute__((address_space(3)))
; DI void gdn_scan_block(LAS unsigned char* lds, int c, const float* P, const GdnPar& pr, float* ORAW, int tid, int lane, int wave) {
;     ...
;             if (lane < 16) {
;                 float cc[32];
;                 const int rowi = cw16 + lane;
; #pragma unroll
;                 for (int tb8 = 0; tb8 < 4; ++tb8) {
;                     float acc[8];
; #pragma unroll
;                     for (int r = 0; r < 8; ++r) acc[r] = RH[(8 * tb8 + r) * 64 + rowi];
; #pragma unroll
;                     for (int jb = 0; jb < tb8; ++jb)
; #pragma unroll
;                         for (int r = 0; r < 8; ++r) { const f32x4 b0 = *(const LAS f32x4*)(BM + (8 * tb8 + r) * 32 + 8 * jb), b1 = *(const LAS f32x4*)(BM + (8 * tb8 + r) * 32 + 8 * jb + 4);
;                             acc[r] -= ((b0[0] * cc[8 * jb] + b0[1] * cc[8 * jb + 1]) + (b0[2] * cc[8 * jb + 2] + b0[3] * cc[8 * jb + 3])) + ((b1[0] * cc[8 * jb + 4] + b1[1] * cc[8 * jb + 5]) + (b1[2] * cc[8 * jb + 6] + b1[3] * cc[8 * jb + 7])); }
; #pragma unroll
;                     for (int rh = 0; rh < 2; ++rh) {
;                         f32x4 d0[4], d1[4];
; #pragma unroll
;                         for (int r = 0; r < 4; ++r) { d0[r] = *(const LAS f32x4*)(BM + (8 * tb8 + 4 * rh + r) * 32 + 8 * tb8); if (rh) d1[r] = *(const LAS f32x4*)(BM + (8 * tb8 + 4 * rh + r) * 32 + 8 * tb8 + 4); }
; #pragma unroll
;                         for (int r = 0; r < 4; ++r) { float av = acc[4 * rh + r];
; #pragma unroll
;                             for (int q = 0; q < 8; ++q) if (q < 4 * rh + r) av -= (q < 4 ? d0[r][q & 3] : d1[r][q & 3]) * cc[8 * tb8 + q];
;                             cc[8 * tb8 + 4 * rh + r] = av; CC[(8 * tb8 + 4 * rh + r) * 64 + rowi] = av; }
;                     }
;                 }
;             }
	v_fma_f32 v104, -v208, v223, v104
	v_fma_f32 v105, -v212, v223, v105
	v_fma_f32 v225, -v209, v224, v104
	v_fma_f32 v105, -v213, v224, v105
	v_fma_f32 v226, -v214, v225, v105
	ds_read_b128 v[100:103], v128 offset:54544
	ds_read_b128 v[208:211], v128 offset:54672
	ds_write2st64_b32 v133, v225, v226 offset0:26 offset1:27
	ds_read2st64_b32 v[80:81], v132 offset0:30 offset1:31
	s_waitcnt lgkmcnt(4)
	v_fma_f32 v130, -v72, v189, v130
	v_fma_f32 v131, -v76, v189, v131
	v_fma_f32 v130, -v73, v190, v130
	v_fma_f32 v131, -v77, v190, v131
	v_fma_f32 v130, -v74, v191, v130
	v_fma_f32 v131, -v78, v191, v131
	v_fma_f32 v130, -v75, v192, v130
	v_fma_f32 v131, -v79, v192, v131
	ds_read_b128 v[212:215], v128 offset:54560
	ds_read_b128 v[72:75], v128 offset:54688
	s_waitcnt lgkmcnt(4)
	v_fma_f32 v130, -v100, v193, v130
	v_fma_f32 v131, -v208, v193, v131
	v_fma_f32 v130, -v101, v194, v130
	v_fma_f32 v131, -v209, v194, v131
	v_fma_f32 v130, -v102, v195, v130
	v_fma_f32 v131, -v210, v195, v131
	v_fma_f32 v130, -v103, v196, v130
	v_fma_f32 v131, -v211, v196, v131
	ds_read_b128 v[76:79], v128 offset:54576
	ds_read_b128 v[100:103], v128 offset:54704
	s_waitcnt lgkmcnt(2)
	v_fma_f32 v130, -v212, v197, v130
	v_fma_f32 v131, -v72, v197, v131
	v_fma_f32 v130, -v213, v198, v130
	v_fma_f32 v131, -v73, v198, v131
	v_fma_f32 v130, -v214, v199, v130
	v_fma_f32 v131, -v74, v199, v131
	v_fma_f32 v130, -v215, v200, v130
	v_fma_f32 v131, -v75, v200, v131
	ds_read_b128 v[208:211], v128 offset:54592
	ds_read_b128 v[212:215], v128 offset:54720
	s_waitcnt lgkmcnt(2)
	v_fma_f32 v130, -v76, v201, v130
	v_fma_f32 v131, -v100, v201, v131
	v_fma_f32 v130, -v77, v202, v130
	v_fma_f32 v131, -v101, v202, v131
	v_fma_f32 v130, -v78, v203, v130
	v_fma_f32 v131, -v102, v203, v131
	v_fma_f32 v130, -v79, v204, v130
	v_fma_f32 v131, -v103, v204, v131
	ds_read_b128 v[72:75], v128 offset:54608
	ds_read_b128 v[76:79], v128 offset:54736
	s_waitcnt lgkmcnt(2)
	v_fma_f32 v130, -v208, v205, v130
	v_fma_f32 v131, -v212, v205, v131
	v_fma_f32 v130, -v209, v216, v130
	v_fma_f32 v131, -v213, v216, v131
	v_fma_f32 v130, -v210, v217, v130
	v_fma_f32 v131, -v214, v217, v131
	v_fma_f32 v130, -v211, v218, v130
	v_fma_f32 v131, -v215, v218, v131
	ds_read_b128 v[100:103], v128 offset:54624
	ds_read_b128 v[208:211], v128 offset:54752
	s_waitcnt lgkmcnt(2)
	v_fma_f32 v130, -v72, v219, v130
	v_fma_f32 v131, -v76, v219, v131
	v_fma_f32 v130, -v73, v220, v130
	v_fma_f32 v131, -v77, v220, v131
	v_fma_f32 v130, -v74, v221, v130
	v_fma_f32 v131, -v78, v221, v131
	v_fma_f32 v130, -v75, v222, v130
	v_fma_f32 v131, -v79, v222, v131
	ds_read_b128 v[212:215], v128 offset:54768
	ds_read_b128 v[72:75], v128 offset:54784
	s_waitcnt lgkmcnt(2)
	v_fma_f32 v130, -v100, v223, v130
	v_fma_f32 v131, -v208, v223, v131
	v_fma_f32 v130, -v101, v224, v130
	v_fma_f32 v131, -v209, v224, v131
	v_fma_f32 v130, -v102, v225, v130
	v_fma_f32 v131, -v210, v225, v131
	v_fma_f32 v227, -v103, v226, v130
	v_fma_f32 v131, -v211, v226, v131
	ds_read_b128 v[76:79], v128 offset:54912
	ds_read_b128 v[100:103], v128 offset:54800
	s_waitcnt lgkmcnt(3)
	v_fma_f32 v228, -v212, v227, v131
	ds_read_b128 v[208:211], v128 offset:54928
	ds_write2st64_b32 v133, v227, v228 offset0:28 offset1:29
	s_waitcnt lgkmcnt(3)
	v_fma_f32 v80, -v72, v189, v80
	v_fma_f32 v81, -v76, v189, v81
	v_fma_f32 v80, -v73, v190, v80
	v_fma_f32 v81, -v77, v190, v81
	v_fma_f32 v80, -v74, v191, v80
	v_fma_f32 v81, -v78, v191, v81
	v_fma_f32 v80, -v75, v192, v80
	v_fma_f32 v81, -v79, v192, v81
	ds_read_b128 v[212:215], v128 offset:54816
	ds_read_b128 v[72:75], v128 offset:54944
	s_waitcnt lgkmcnt(3)
	v_fma_f32 v80, -v100, v193, v80
	v_fma_f32 v81, -v208, v193, v81
	v_fma_f32 v80, -v101, v194, v80
	v_fma_f32 v81, -v209, v194, v81
	v_fma_f32 v80, -v102, v195, v80
	v_fma_f32 v81, -v210, v195, v81
	v_fma_f32 v80, -v103, v196, v80
	v_fma_f32 v81, -v211, v196, v81
	ds_read_b128 v[76:79], v128 offset:54832
	ds_read_b128 v[100:103], v128 offset:54960
	s_waitcnt lgkmcnt(2)
	v_fma_f32 v80, -v212, v197, v80
	v_fma_f32 v81, -v72, v197, v81
	v_fma_f32 v80, -v213, v198, v80
	v_fma_f32 v81, -v73, v198, v81
	v_fma_f32 v80, -v214, v199, v80
	v_fma_f32 v81, -v74, v199, v81
	v_fma_f32 v80, -v215, v200, v80
	v_fma_f32 v81, -v75, v200, v81
	ds_read_b128 v[208:211], v128 offset:54848
	ds_read_b128 v[212:215], v128 offset:54976
	s_waitcnt lgkmcnt(2)
	v_fma_f32 v80, -v76, v201, v80
	v_fma_f32 v81, -v100, v201, v81
	v_fma_f32 v80, -v77, v202, v80
	v_fma_f32 v81, -v101, v202, v81
	v_fma_f32 v80, -v78, v203, v80
	v_fma_f32 v81, -v102, v203, v81
	v_fma_f32 v80, -v79, v204, v80
	v_fma_f32 v81, -v103, v204, v81
	ds_read_b128 v[72:75], v128 offset:54864
	ds_read_b128 v[76:79], v128 offset:54992
	s_waitcnt lgkmcnt(2)
	v_fma_f32 v80, -v208, v205, v80
	v_fma_f32 v81, -v212, v205, v81
	v_fma_f32 v80, -v209, v216, v80
	v_fma_f32 v81, -v213, v216, v81
	v_fma_f32 v80, -v210, v217, v80
	v_fma_f32 v81, -v214, v217, v81
	v_fma_f32 v80, -v211, v218, v80
	v_fma_f32 v81, -v215, v218, v81
	ds_read_b128 v[100:103], v128 offset:54880
	ds_read_b128 v[208:211], v128 offset:55008
	s_waitcnt lgkmcnt(2)
	v_fma_f32 v80, -v72, v219, v80
	v_fma_f32 v81, -v76, v219, v81
	v_fma_f32 v80, -v73, v220, v80
	v_fma_f32 v81, -v77, v220, v81
	v_fma_f32 v80, -v74, v221, v80
	v_fma_f32 v81, -v78, v221, v81
	v_fma_f32 v80, -v75, v222, v80
	v_fma_f32 v81, -v79, v222, v81
	ds_read_b128 v[212:215], v128 offset:54896
	ds_read_b128 v[72:75], v128 offset:55024
	s_waitcnt lgkmcnt(2)
	v_fma_f32 v80, -v100, v223, v80
	v_fma_f32 v81, -v208, v223, v81
	v_fma_f32 v80, -v101, v224, v80
	v_fma_f32 v81, -v209, v224, v81
	v_fma_f32 v80, -v102, v225, v80
	v_fma_f32 v81, -v210, v225, v81
	v_fma_f32 v80, -v103, v226, v80
	v_fma_f32 v81, -v211, v226, v81
	s_waitcnt lgkmcnt(0)
	v_fma_f32 v80, -v212, v227, v80
	v_fma_f32 v81, -v72, v227, v81
	v_fma_f32 v229, -v213, v228, v80
	v_fma_f32 v81, -v73, v228, v81
	v_fma_f32 v106, -v74, v229, v81
	ds_write2st64_b32 v133, v229, v106 offset0:30 offset1:31
	s_branch .LBB0_888
